# B1 queue chunk-MLP item: eight serialized staging loads issued together (one memory round trip)
# baseline (speedup 1.0000x reference)
.LBB0_605:
	s_or_b64 exec, exec, s[0:1]
	s_waitcnt lgkmcnt(0)
	s_barrier
	ds_read_b32 v1, v131 offset:228
	s_movk_i32 s0, 0x2ff
	s_waitcnt lgkmcnt(0)
	s_barrier
	v_cmp_lt_i32_e32 vcc, s0, v1
	v_readfirstlane_b32 s20, v1
	s_mov_b64 s[0:1], -1
	s_cbranch_vccnz .LBB0_600
	s_cmpk_gt_i32 s20, 0xff
	s_cbranch_scc0 .LBB0_702
	s_cmpk_gt_u32 s20, 0x1ff
	s_cbranch_scc0 .LBB0_612
	v_mov_b32_e32 v1, v0
	ds_read_b64 v[2:3], v131 offset:88
	s_and_b32 s0, s20, 3
	v_readlane_b32 s4, v254, 63
	s_or_b32 s10, s0, s4
	s_lshl_b32 s96, s10, 14
	s_lshl_b32 s1, s20, 5
	s_waitcnt lgkmcnt(0)
	v_readfirstlane_b32 s7, v2
	s_lshl_b64 s[4:5], s[96:97], 2
	v_lshlrev_b32_e32 v2, 2, v1
	v_readfirstlane_b32 s6, v3
	s_add_u32 s4, s7, s4
	v_and_b32_e32 v2, 0x7c, v2
	v_ashrrev_i32_e32 v3, 5, v1
	s_addc_u32 s5, s6, s5
	v_lshlrev_b32_e32 v130, 2, v2
	s_waitcnt vmcnt(9)
	v_lshlrev_b32_e32 v6, 7, v3
	v_lshl_add_u64 v[4:5], s[4:5], 0, v[130:131]
	v_ashrrev_i32_e32 v7, 31, v6
	v_lshl_add_u64 v[6:7], v[6:7], 2, v[4:5]
	s_barrier
	v_lshl_add_u32 v2, v2, 1, v212
	v_lshl_add_u32 v30, v3, 9, v130
	v_mul_u32_u24_e32 v31, 0x110, v3
	v_add_u32_e32 v31, v31, v2
	global_load_dwordx4 v[6:9], v30, s[4:5]
	s_add_u32 s4, s4, 0x2000
	s_addc_u32 s5, s5, 0
	global_load_dwordx4 v[10:13], v30, s[4:5]
	s_add_u32 s4, s4, 0x2000
	s_addc_u32 s5, s5, 0
	global_load_dwordx4 v[14:17], v30, s[4:5]
	s_add_u32 s4, s4, 0x2000
	s_addc_u32 s5, s5, 0
	global_load_dwordx4 v[18:21], v30, s[4:5]
	s_add_u32 s4, s4, 0x2000
	s_addc_u32 s5, s5, 0
	global_load_dwordx4 v[22:25], v30, s[4:5]
	s_add_u32 s4, s4, 0x2000
	s_addc_u32 s5, s5, 0
	global_load_dwordx4 v[26:29], v30, s[4:5]
	s_add_u32 s4, s4, 0x2000
	s_addc_u32 s5, s5, 0
	global_load_dwordx4 v[32:35], v30, s[4:5]
	s_add_u32 s4, s4, 0x2000
	s_addc_u32 s5, s5, 0
	global_load_dwordx4 v[36:39], v30, s[4:5]
	s_movk_i32 s6, 0x110
	s_waitcnt vmcnt(7)
	v_cvt_pk_bf16_f32 v6, v6, v7
	v_cvt_pk_bf16_f32 v7, v8, v9
	ds_write_b64 v31, v[6:7]
	s_waitcnt vmcnt(6)
	v_cvt_pk_bf16_f32 v10, v10, v11
	v_cvt_pk_bf16_f32 v11, v12, v13
	ds_write_b64 v31, v[10:11] offset:4352
	s_waitcnt vmcnt(5)
	v_cvt_pk_bf16_f32 v14, v14, v15
	v_cvt_pk_bf16_f32 v15, v16, v17
	ds_write_b64 v31, v[14:15] offset:8704
	s_waitcnt vmcnt(4)
	v_cvt_pk_bf16_f32 v18, v18, v19
	v_cvt_pk_bf16_f32 v19, v20, v21
	ds_write_b64 v31, v[18:19] offset:13056
	s_waitcnt vmcnt(3)
	v_cvt_pk_bf16_f32 v22, v22, v23
	v_cvt_pk_bf16_f32 v23, v24, v25
	ds_write_b64 v31, v[22:23] offset:17408
	s_waitcnt vmcnt(2)
	v_cvt_pk_bf16_f32 v26, v26, v27
	v_cvt_pk_bf16_f32 v27, v28, v29
	ds_write_b64 v31, v[26:27] offset:21760
	s_waitcnt vmcnt(1)
	v_cvt_pk_bf16_f32 v32, v32, v33
	v_cvt_pk_bf16_f32 v33, v34, v35
	ds_write_b64 v31, v[32:33] offset:26112
	s_waitcnt vmcnt(0)
	v_cvt_pk_bf16_f32 v36, v36, v37
	v_cvt_pk_bf16_f32 v37, v38, v39
	ds_write_b64 v31, v[36:37] offset:30464
	s_lshl_b32 s11, s0, 6
	v_mov_b32_e32 v2, v0
	s_movk_i32 s0, 0x800
	s_and_b32 s12, s1, 0x1f80
	s_nop 0
	v_cmp_gt_i32_e32 vcc, s0, v2
	s_and_saveexec_b64 s[0:1], vcc
	s_cbranch_execz .LBB0_611
	s_mul_i32 s4, s12, 0x2200
	s_add_u32 s4, s28, s4
	s_addc_u32 s5, s29, 0
	s_lshl_b32 s6, s11, 2
	s_add_u32 s4, s4, s6
	s_addc_u32 s5, s5, 0
	v_lshlrev_b32_e32 v3, 2, v2
	s_mov_b64 s[6:7], 0
